# EpiGateUp hand-written: packed broadcasts, rs^2 folded into rcp argument, saddr SS loads/HID stores (343 vs 525 instr)
# speedup vs baseline: 1.0033x; 1.0033x over previous
; DI u32x4 pk8(f32x4 a, f32x4 b) { u32x4 w; w.x = pk2(a[0], a[1]); w.y = pk2(a[2], a[3]); w.z = pk2(b[0], b[1]); w.w = pk2(b[2], b[3]); return w; }
; DI float row_rstd(const float* SS, int row) { return rsqrtf(SS[row] * (1.0f / 1024.0f) + 1e-6f); }
;     DI void operator()(const Acc& acc, const pg8::Unit& u, int wr, int wc, int fr, int fq) const {
;         const int colb = u.pn * 128 + wc * 32 + fq * 8;
;         float rsv[2][4];
; #pragma unroll
;         for (int ai = 0; ai < 2; ++ai)
; #pragma unroll
;             for (int m = 0; m < 4; ++m) rsv[ai][m] = row_rstd(SS, u.pm * 256 + ai * 128 + wr * 64 + m * 16 + fr);
; #pragma unroll
;         for (int ai = 0; ai < 2; ++ai)
; #pragma unroll
;             for (int m = 0; m < 4; ++m) {
;                 const int row = u.pm * 256 + ai * 128 + wr * 64 + m * 16 + fr;
;                 const float rs = rsv[ai][m];
;                 f32x4 h0, h1;
;                 const float rs2 = rs * rs, nrl = -rs * LOG2E;
; #pragma unroll
;                 for (int i = 0; i < 4; ++i) {
;                     const float a0 = acc[ai][0][m][0][i], a1 = acc[ai][0][m][1][i];
;                     h0[i] = (a0 * acc[ai][1][m][0][i]) * rs2 * __builtin_amdgcn_rcpf(1.0f + __builtin_amdgcn_exp2f(a0 * nrl));
;                     h1[i] = (a1 * acc[ai][1][m][1][i]) * rs2 * __builtin_amdgcn_rcpf(1.0f + __builtin_amdgcn_exp2f(a1 * nrl));
;                 }
;                 __builtin_nontemporal_store(pk8(h0, h1), (u32x4*)(HID + (size_t)row * FH + colb));
;             }
.LBB0_612:
	v_lshl_add_u32 v160, s4, 8, v165
	v_lshlrev_b32_e32 v185, 2, v160
	global_load_dword v146, v185, s[50:51]
	global_load_dword v147, v185, s[50:51] offset:64
	global_load_dword v148, v185, s[50:51] offset:128
	global_load_dword v149, v185, s[50:51] offset:192
	global_load_dword v150, v185, s[50:51] offset:512
	global_load_dword v151, v185, s[50:51] offset:576
	global_load_dword v152, v185, s[50:51] offset:640
	global_load_dword v153, v185, s[50:51] offset:704
	v_lshl_or_b32 v181, s5, 7, v167
	v_lshlrev_b32_e32 v181, 1, v181
	v_mad_u32_u24 v183, v160, s83, v181
	v_pk_mul_f32 v[122:123], v[126:127], v[122:123]
	v_pk_mul_f32 v[124:125], v[128:129], v[124:125]
	v_pk_mul_f32 v[114:115], v[118:119], v[114:115]
	v_pk_mul_f32 v[116:117], v[120:121], v[116:117]
	v_pk_mul_f32 v[106:107], v[110:111], v[106:107]
	v_pk_mul_f32 v[108:109], v[112:113], v[108:109]
	v_pk_mul_f32 v[98:99], v[102:103], v[98:99]
	v_pk_mul_f32 v[100:101], v[104:105], v[100:101]
	v_pk_mul_f32 v[90:91], v[94:95], v[90:91]
	v_pk_mul_f32 v[92:93], v[96:97], v[92:93]
	v_pk_mul_f32 v[82:83], v[86:87], v[82:83]
	v_pk_mul_f32 v[84:85], v[88:89], v[84:85]
	v_pk_mul_f32 v[74:75], v[78:79], v[74:75]
	v_pk_mul_f32 v[76:77], v[80:81], v[76:77]
	v_pk_mul_f32 v[66:67], v[70:71], v[66:67]
	v_pk_mul_f32 v[68:69], v[72:73], v[68:69]
	v_pk_mul_f32 v[58:59], v[62:63], v[58:59]
	v_pk_mul_f32 v[60:61], v[64:65], v[60:61]
	v_pk_mul_f32 v[50:51], v[54:55], v[50:51]
	v_pk_mul_f32 v[52:53], v[56:57], v[52:53]
	v_pk_mul_f32 v[42:43], v[46:47], v[42:43]
	v_pk_mul_f32 v[44:45], v[48:49], v[44:45]
	v_pk_mul_f32 v[34:35], v[38:39], v[34:35]
	v_pk_mul_f32 v[36:37], v[40:41], v[36:37]
	v_pk_mul_f32 v[26:27], v[30:31], v[26:27]
	v_pk_mul_f32 v[28:29], v[32:33], v[28:29]
	v_pk_mul_f32 v[18:19], v[22:23], v[18:19]
	v_pk_mul_f32 v[20:21], v[24:25], v[20:21]
	v_pk_mul_f32 v[10:11], v[14:15], v[10:11]
	v_pk_mul_f32 v[12:13], v[16:17], v[12:13]
	v_pk_mul_f32 v[2:3], v[6:7], v[2:3]
	v_pk_mul_f32 v[4:5], v[8:9], v[4:5]
	s_andn2_b64 vcc, exec, s[0:1]
	s_mov_b64 s[0:1], -1
	s_waitcnt vmcnt(0)
	v_fmamk_f32 v232, v146, 0x3a800000, v171
	v_fmamk_f32 v234, v147, 0x3a800000, v171
	v_fmamk_f32 v236, v148, 0x3a800000, v171
	v_fmamk_f32 v238, v149, 0x3a800000, v171
	v_fmamk_f32 v240, v150, 0x3a800000, v171
	v_fmamk_f32 v242, v151, 0x3a800000, v171
	v_fmamk_f32 v244, v152, 0x3a800000, v171
	v_fmamk_f32 v246, v153, 0x3a800000, v171
	v_rsq_f32_e32 v154, v232
	v_rsq_f32_e32 v155, v234
	v_rsq_f32_e32 v156, v236
	v_rsq_f32_e32 v157, v238
	v_rsq_f32_e32 v158, v240
	v_rsq_f32_e32 v159, v242
	v_rsq_f32_e32 v160, v244
	v_rsq_f32_e32 v161, v246
	v_mul_f32_e32 v172, 0xbfb8aa3b, v154
	v_mul_f32_e32 v174, 0xbfb8aa3b, v155
	v_mul_f32_e32 v176, 0xbfb8aa3b, v156
	v_mul_f32_e32 v178, 0xbfb8aa3b, v157
	v_mul_f32_e32 v180, 0xbfb8aa3b, v158
	v_mul_f32_e32 v182, 0xbfb8aa3b, v159
	v_mul_f32_e32 v184, 0xbfb8aa3b, v160
	v_mul_f32_e32 v230, 0xbfb8aa3b, v161
	v_pk_mul_f32 v[126:127], v[126:127], v[172:173] op_sel_hi:[1,0]
	v_pk_mul_f32 v[128:129], v[128:129], v[172:173] op_sel_hi:[1,0]
	v_pk_mul_f32 v[118:119], v[118:119], v[172:173] op_sel_hi:[1,0]
	v_pk_mul_f32 v[120:121], v[120:121], v[172:173] op_sel_hi:[1,0]
	v_exp_f32_e32 v126, v126
	v_exp_f32_e32 v127, v127
	v_exp_f32_e32 v128, v128
	v_exp_f32_e32 v129, v129
	v_exp_f32_e32 v118, v118
	v_exp_f32_e32 v119, v119
	v_exp_f32_e32 v120, v120
	v_exp_f32_e32 v121, v121
	v_pk_fma_f32 v[126:127], v[126:127], v[232:233], v[232:233] op_sel_hi:[1,0,0]
	v_pk_fma_f32 v[128:129], v[128:129], v[232:233], v[232:233] op_sel_hi:[1,0,0]
	v_pk_fma_f32 v[118:119], v[118:119], v[232:233], v[232:233] op_sel_hi:[1,0,0]
	v_pk_fma_f32 v[120:121], v[120:121], v[232:233], v[232:233] op_sel_hi:[1,0,0]
	v_rcp_f32_e32 v126, v126
	v_rcp_f32_e32 v127, v127
	v_rcp_f32_e32 v128, v128
	v_rcp_f32_e32 v129, v129
	v_rcp_f32_e32 v118, v118
	v_rcp_f32_e32 v119, v119
	v_rcp_f32_e32 v120, v120
	v_rcp_f32_e32 v121, v121
	v_pk_mul_f32 v[122:123], v[122:123], v[126:127]
	v_pk_mul_f32 v[124:125], v[124:125], v[128:129]
	v_pk_mul_f32 v[114:115], v[114:115], v[118:119]
	v_pk_mul_f32 v[116:117], v[116:117], v[120:121]
	v_cvt_pk_bf16_f32 v122, v122, v123
	v_cvt_pk_bf16_f32 v123, v124, v125
	v_cvt_pk_bf16_f32 v124, v114, v115
	v_cvt_pk_bf16_f32 v125, v116, v117
	global_store_dwordx4 v183, v[122:125], s[24:25] nt
	v_add_u32_e32 v183, 0x16000, v183
	v_pk_mul_f32 v[110:111], v[110:111], v[174:175] op_sel_hi:[1,0]
	v_pk_mul_f32 v[112:113], v[112:113], v[174:175] op_sel_hi:[1,0]
	v_pk_mul_f32 v[102:103], v[102:103], v[174:175] op_sel_hi:[1,0]
	v_pk_mul_f32 v[104:105], v[104:105], v[174:175] op_sel_hi:[1,0]
	v_exp_f32_e32 v110, v110
	v_exp_f32_e32 v111, v111
	v_exp_f32_e32 v112, v112
	v_exp_f32_e32 v113, v113
	v_exp_f32_e32 v102, v102
	v_exp_f32_e32 v103, v103
	v_exp_f32_e32 v104, v104
	v_exp_f32_e32 v105, v105
	v_pk_fma_f32 v[110:111], v[110:111], v[234:235], v[234:235] op_sel_hi:[1,0,0]
	v_pk_fma_f32 v[112:113], v[112:113], v[234:235], v[234:235] op_sel_hi:[1,0,0]
	v_pk_fma_f32 v[102:103], v[102:103], v[234:235], v[234:235] op_sel_hi:[1,0,0]
	v_pk_fma_f32 v[104:105], v[104:105], v[234:235], v[234:235] op_sel_hi:[1,0,0]
	v_rcp_f32_e32 v110, v110
	v_rcp_f32_e32 v111, v111
	v_rcp_f32_e32 v112, v112
	v_rcp_f32_e32 v113, v113
	v_rcp_f32_e32 v102, v102
	v_rcp_f32_e32 v103, v103
	v_rcp_f32_e32 v104, v104
	v_rcp_f32_e32 v105, v105
	v_pk_mul_f32 v[106:107], v[106:107], v[110:111]
	v_pk_mul_f32 v[108:109], v[108:109], v[112:113]
	v_pk_mul_f32 v[98:99], v[98:99], v[102:103]
	v_pk_mul_f32 v[100:101], v[100:101], v[104:105]
	v_cvt_pk_bf16_f32 v106, v106, v107
	v_cvt_pk_bf16_f32 v107, v108, v109
	v_cvt_pk_bf16_f32 v108, v98, v99
	v_cvt_pk_bf16_f32 v109, v100, v101
; DI u32x4 pk8(f32x4 a, f32x4 b) { u32x4 w; w.x = pk2(a[0], a[1]); w.y = pk2(a[2], a[3]); w.z = pk2(b[0], b[1]); w.w = pk2(b[2], b[3]); return w; }
; DI float row_rstd(const float* SS, int row) { return rsqrtf(SS[row] * (1.0f / 1024.0f) + 1e-6f); }
;     DI void operator()(const Acc& acc, const pg8::Unit& u, int wr, int wc, int fr, int fq) const {
;         const int colb = u.pn * 128 + wc * 32 + fq * 8;
;         float rsv[2][4];
; #pragma unroll
;         for (int ai = 0; ai < 2; ++ai)
; #pragma unroll
;             for (int m = 0; m < 4; ++m) rsv[ai][m] = row_rstd(SS, u.pm * 256 + ai * 128 + wr * 64 + m * 16 + fr);
; #pragma unroll
;         for (int ai = 0; ai < 2; ++ai)
; #pragma unroll
;             for (int m = 0; m < 4; ++m) {
;                 const int row = u.pm * 256 + ai * 128 + wr * 64 + m * 16 + fr;
;                 const float rs = rsv[ai][m];
;                 f32x4 h0, h1;
;                 const float rs2 = rs * rs, nrl = -rs * LOG2E;
; #pragma unroll
;                 for (int i = 0; i < 4; ++i) {
;                     const float a0 = acc[ai][0][m][0][i], a1 = acc[ai][0][m][1][i];
;                     h0[i] = (a0 * acc[ai][1][m][0][i]) * rs2 * __builtin_amdgcn_rcpf(1.0f + __builtin_amdgcn_exp2f(a0 * nrl));
;                     h1[i] = (a1 * acc[ai][1][m][1][i]) * rs2 * __builtin_amdgcn_rcpf(1.0f + __builtin_amdgcn_exp2f(a1 * nrl));
;                 }
;                 __builtin_nontemporal_store(pk8(h0, h1), (u32x4*)(HID + (size_t)row * FH + colb));
;             }
	global_store_dwordx4 v183, v[106:109], s[24:25] nt
	v_add_u32_e32 v183, 0x16000, v183
	v_pk_mul_f32 v[94:95], v[94:95], v[176:177] op_sel_hi:[1,0]
	v_pk_mul_f32 v[96:97], v[96:97], v[176:177] op_sel_hi:[1,0]
	v_pk_mul_f32 v[86:87], v[86:87], v[176:177] op_sel_hi:[1,0]
	v_pk_mul_f32 v[88:89], v[88:89], v[176:177] op_sel_hi:[1,0]
	v_exp_f32_e32 v94, v94
	v_exp_f32_e32 v95, v95
	v_exp_f32_e32 v96, v96
	v_exp_f32_e32 v97, v97
	v_exp_f32_e32 v86, v86
	v_exp_f32_e32 v87, v87
	v_exp_f32_e32 v88, v88
	v_exp_f32_e32 v89, v89
	v_pk_fma_f32 v[94:95], v[94:95], v[236:237], v[236:237] op_sel_hi:[1,0,0]
	v_pk_fma_f32 v[96:97], v[96:97], v[236:237], v[236:237] op_sel_hi:[1,0,0]
	v_pk_fma_f32 v[86:87], v[86:87], v[236:237], v[236:237] op_sel_hi:[1,0,0]
	v_pk_fma_f32 v[88:89], v[88:89], v[236:237], v[236:237] op_sel_hi:[1,0,0]
	v_rcp_f32_e32 v94, v94
	v_rcp_f32_e32 v95, v95
	v_rcp_f32_e32 v96, v96
	v_rcp_f32_e32 v97, v97
	v_rcp_f32_e32 v86, v86
	v_rcp_f32_e32 v87, v87
	v_rcp_f32_e32 v88, v88
	v_rcp_f32_e32 v89, v89
	v_pk_mul_f32 v[90:91], v[90:91], v[94:95]
	v_pk_mul_f32 v[92:93], v[92:93], v[96:97]
	v_pk_mul_f32 v[82:83], v[82:83], v[86:87]
	v_pk_mul_f32 v[84:85], v[84:85], v[88:89]
	v_cvt_pk_bf16_f32 v90, v90, v91
	v_cvt_pk_bf16_f32 v91, v92, v93
	v_cvt_pk_bf16_f32 v92, v82, v83
	v_cvt_pk_bf16_f32 v93, v84, v85
	global_store_dwordx4 v183, v[90:93], s[24:25] nt
	v_add_u32_e32 v183, 0x16000, v183
	v_pk_mul_f32 v[78:79], v[78:79], v[178:179] op_sel_hi:[1,0]
	v_pk_mul_f32 v[80:81], v[80:81], v[178:179] op_sel_hi:[1,0]
	v_pk_mul_f32 v[70:71], v[70:71], v[178:179] op_sel_hi:[1,0]
	v_pk_mul_f32 v[72:73], v[72:73], v[178:179] op_sel_hi:[1,0]
	v_exp_f32_e32 v78, v78
	v_exp_f32_e32 v79, v79
	v_exp_f32_e32 v80, v80
	v_exp_f32_e32 v81, v81
	v_exp_f32_e32 v70, v70
	v_exp_f32_e32 v71, v71
	v_exp_f32_e32 v72, v72
	v_exp_f32_e32 v73, v73
	v_pk_fma_f32 v[78:79], v[78:79], v[238:239], v[238:239] op_sel_hi:[1,0,0]
	v_pk_fma_f32 v[80:81], v[80:81], v[238:239], v[238:239] op_sel_hi:[1,0,0]
	v_pk_fma_f32 v[70:71], v[70:71], v[238:239], v[238:239] op_sel_hi:[1,0,0]
	v_pk_fma_f32 v[72:73], v[72:73], v[238:239], v[238:239] op_sel_hi:[1,0,0]
	v_rcp_f32_e32 v78, v78
	v_rcp_f32_e32 v79, v79
	v_rcp_f32_e32 v80, v80
	v_rcp_f32_e32 v81, v81
	v_rcp_f32_e32 v70, v70
	v_rcp_f32_e32 v71, v71
	v_rcp_f32_e32 v72, v72
	v_rcp_f32_e32 v73, v73
	v_pk_mul_f32 v[74:75], v[74:75], v[78:79]
	v_pk_mul_f32 v[76:77], v[76:77], v[80:81]
	v_pk_mul_f32 v[66:67], v[66:67], v[70:71]
	v_pk_mul_f32 v[68:69], v[68:69], v[72:73]
	v_cvt_pk_bf16_f32 v74, v74, v75
	v_cvt_pk_bf16_f32 v75, v76, v77
	v_cvt_pk_bf16_f32 v76, v66, v67
	v_cvt_pk_bf16_f32 v77, v68, v69
	global_store_dwordx4 v183, v[74:77], s[24:25] nt
	v_add_u32_e32 v183, 0x6e000, v183
	v_pk_mul_f32 v[62:63], v[62:63], v[180:181] op_sel_hi:[1,0]
	v_pk_mul_f32 v[64:65], v[64:65], v[180:181] op_sel_hi:[1,0]
	v_pk_mul_f32 v[54:55], v[54:55], v[180:181] op_sel_hi:[1,0]
	v_pk_mul_f32 v[56:57], v[56:57], v[180:181] op_sel_hi:[1,0]
	v_exp_f32_e32 v62, v62
	v_exp_f32_e32 v63, v63
	v_exp_f32_e32 v64, v64
	v_exp_f32_e32 v65, v65
	v_exp_f32_e32 v54, v54
	v_exp_f32_e32 v55, v55
	v_exp_f32_e32 v56, v56
	v_exp_f32_e32 v57, v57
	v_pk_fma_f32 v[62:63], v[62:63], v[240:241], v[240:241] op_sel_hi:[1,0,0]
	v_pk_fma_f32 v[64:65], v[64:65], v[240:241], v[240:241] op_sel_hi:[1,0,0]
	v_pk_fma_f32 v[54:55], v[54:55], v[240:241], v[240:241] op_sel_hi:[1,0,0]
	v_pk_fma_f32 v[56:57], v[56:57], v[240:241], v[240:241] op_sel_hi:[1,0,0]
	v_rcp_f32_e32 v62, v62
	v_rcp_f32_e32 v63, v63
	v_rcp_f32_e32 v64, v64
	v_rcp_f32_e32 v65, v65
	v_rcp_f32_e32 v54, v54
	v_rcp_f32_e32 v55, v55
	v_rcp_f32_e32 v56, v56
	v_rcp_f32_e32 v57, v57
	v_pk_mul_f32 v[58:59], v[58:59], v[62:63]
	v_pk_mul_f32 v[60:61], v[60:61], v[64:65]
	v_pk_mul_f32 v[50:51], v[50:51], v[54:55]
	v_pk_mul_f32 v[52:53], v[52:53], v[56:57]
	v_cvt_pk_bf16_f32 v58, v58, v59
	v_cvt_pk_bf16_f32 v59, v60, v61
	v_cvt_pk_bf16_f32 v60, v50, v51
	v_cvt_pk_bf16_f32 v61, v52, v53
	global_store_dwordx4 v183, v[58:61], s[24:25] nt
; DI u32x4 pk8(f32x4 a, f32x4 b) { u32x4 w; w.x = pk2(a[0], a[1]); w.y = pk2(a[2], a[3]); w.z = pk2(b[0], b[1]); w.w = pk2(b[2], b[3]); return w; }
; #define PG8_BAR __builtin_amdgcn_s_barrier()
; DI float row_rstd(const float* SS, int row) { return rsqrtf(SS[row] * (1.0f / 1024.0f) + 1e-6f); }
; template <class Epi, bool ALIGN_EPI>
; __device__ __forceinline__ void gemm_phase(LAS unsigned char* lds, const Gemm g, const StaticOrder& S, const Epi& E) {
;     ...
;         if (!has_next) break;
; #pragma unroll
;         for (int a = 0; a < 2; ++a)
; #pragma unroll
;             for (int b = 0; b < 2; ++b)
; #pragma unroll
;                 for (int m = 0; m < 4; ++m)
; #pragma unroll
;                     for (int n = 0; n < 2; ++n) acc[a][b][m][n] = (f32x4){0.f, 0.f, 0.f, 0.f};
;         cur = nxt; cA = nA; cB = nB; ++ui;
;         if constexpr (ALIGN_EPI) { if (wr == 1) PG8_BAR; }
;     DI void operator()(const Acc& acc, const pg8::Unit& u, int wr, int wc, int fr, int fq) const {
;         const int colb = u.pn * 128 + wc * 32 + fq * 8;
;         float rsv[2][4];
; #pragma unroll
;         for (int ai = 0; ai < 2; ++ai)
; #pragma unroll
;             for (int m = 0; m < 4; ++m) rsv[ai][m] = row_rstd(SS, u.pm * 256 + ai * 128 + wr * 64 + m * 16 + fr);
; #pragma unroll
;         for (int ai = 0; ai < 2; ++ai)
; #pragma unroll
;             for (int m = 0; m < 4; ++m) {
;                 const int row = u.pm * 256 + ai * 128 + wr * 64 + m * 16 + fr;
;                 const float rs = rsv[ai][m];
;                 f32x4 h0, h1;
;                 const float rs2 = rs * rs, nrl = -rs * LOG2E;
; #pragma unroll
;                 for (int i = 0; i < 4; ++i) {
;                     const float a0 = acc[ai][0][m][0][i], a1 = acc[ai][0][m][1][i];
;                     h0[i] = (a0 * acc[ai][1][m][0][i]) * rs2 * __builtin_amdgcn_rcpf(1.0f + __builtin_amdgcn_exp2f(a0 * nrl));
;                     h1[i] = (a1 * acc[ai][1][m][1][i]) * rs2 * __builtin_amdgcn_rcpf(1.0f + __builtin_amdgcn_exp2f(a1 * nrl));
;                 }
;                 __builtin_nontemporal_store(pk8(h0, h1), (u32x4*)(HID + (size_t)row * FH + colb));
;             }
	v_add_u32_e32 v183, 0x16000, v183
	v_pk_mul_f32 v[46:47], v[46:47], v[182:183] op_sel_hi:[1,0]
	v_pk_mul_f32 v[48:49], v[48:49], v[182:183] op_sel_hi:[1,0]
	v_pk_mul_f32 v[38:39], v[38:39], v[182:183] op_sel_hi:[1,0]
	v_pk_mul_f32 v[40:41], v[40:41], v[182:183] op_sel_hi:[1,0]
	v_exp_f32_e32 v46, v46
	v_exp_f32_e32 v47, v47
	v_exp_f32_e32 v48, v48
	v_exp_f32_e32 v49, v49
	v_exp_f32_e32 v38, v38
	v_exp_f32_e32 v39, v39
	v_exp_f32_e32 v40, v40
	v_exp_f32_e32 v41, v41
	v_pk_fma_f32 v[46:47], v[46:47], v[242:243], v[242:243] op_sel_hi:[1,0,0]
	v_pk_fma_f32 v[48:49], v[48:49], v[242:243], v[242:243] op_sel_hi:[1,0,0]
	v_pk_fma_f32 v[38:39], v[38:39], v[242:243], v[242:243] op_sel_hi:[1,0,0]
	v_pk_fma_f32 v[40:41], v[40:41], v[242:243], v[242:243] op_sel_hi:[1,0,0]
	v_rcp_f32_e32 v46, v46
	v_rcp_f32_e32 v47, v47
	v_rcp_f32_e32 v48, v48
	v_rcp_f32_e32 v49, v49
	v_rcp_f32_e32 v38, v38
	v_rcp_f32_e32 v39, v39
	v_rcp_f32_e32 v40, v40
	v_rcp_f32_e32 v41, v41
	v_pk_mul_f32 v[42:43], v[42:43], v[46:47]
	v_pk_mul_f32 v[44:45], v[44:45], v[48:49]
	v_pk_mul_f32 v[34:35], v[34:35], v[38:39]
	v_pk_mul_f32 v[36:37], v[36:37], v[40:41]
	v_cvt_pk_bf16_f32 v42, v42, v43
	v_cvt_pk_bf16_f32 v43, v44, v45
	v_cvt_pk_bf16_f32 v44, v34, v35
	v_cvt_pk_bf16_f32 v45, v36, v37
	global_store_dwordx4 v183, v[42:45], s[24:25] nt
	v_add_u32_e32 v183, 0x16000, v183
	v_pk_mul_f32 v[30:31], v[30:31], v[184:185] op_sel_hi:[1,0]
	v_pk_mul_f32 v[32:33], v[32:33], v[184:185] op_sel_hi:[1,0]
	v_pk_mul_f32 v[22:23], v[22:23], v[184:185] op_sel_hi:[1,0]
	v_pk_mul_f32 v[24:25], v[24:25], v[184:185] op_sel_hi:[1,0]
	v_exp_f32_e32 v30, v30
	v_exp_f32_e32 v31, v31
	v_exp_f32_e32 v32, v32
	v_exp_f32_e32 v33, v33
	v_exp_f32_e32 v22, v22
	v_exp_f32_e32 v23, v23
	v_exp_f32_e32 v24, v24
	v_exp_f32_e32 v25, v25
	v_pk_fma_f32 v[30:31], v[30:31], v[244:245], v[244:245] op_sel_hi:[1,0,0]
	v_pk_fma_f32 v[32:33], v[32:33], v[244:245], v[244:245] op_sel_hi:[1,0,0]
	v_pk_fma_f32 v[22:23], v[22:23], v[244:245], v[244:245] op_sel_hi:[1,0,0]
	v_pk_fma_f32 v[24:25], v[24:25], v[244:245], v[244:245] op_sel_hi:[1,0,0]
	v_rcp_f32_e32 v30, v30
	v_rcp_f32_e32 v31, v31
	v_rcp_f32_e32 v32, v32
	v_rcp_f32_e32 v33, v33
	v_rcp_f32_e32 v22, v22
	v_rcp_f32_e32 v23, v23
	v_rcp_f32_e32 v24, v24
	v_rcp_f32_e32 v25, v25
	v_pk_mul_f32 v[26:27], v[26:27], v[30:31]
	v_pk_mul_f32 v[28:29], v[28:29], v[32:33]
	v_pk_mul_f32 v[18:19], v[18:19], v[22:23]
	v_pk_mul_f32 v[20:21], v[20:21], v[24:25]
	v_cvt_pk_bf16_f32 v26, v26, v27
	v_cvt_pk_bf16_f32 v27, v28, v29
	v_cvt_pk_bf16_f32 v28, v18, v19
	v_cvt_pk_bf16_f32 v29, v20, v21
	global_store_dwordx4 v183, v[26:29], s[24:25] nt
	v_add_u32_e32 v183, 0x16000, v183
	v_pk_mul_f32 v[14:15], v[14:15], v[230:231] op_sel_hi:[1,0]
	v_pk_mul_f32 v[16:17], v[16:17], v[230:231] op_sel_hi:[1,0]
	v_pk_mul_f32 v[6:7], v[6:7], v[230:231] op_sel_hi:[1,0]
	v_pk_mul_f32 v[8:9], v[8:9], v[230:231] op_sel_hi:[1,0]
	v_exp_f32_e32 v14, v14
	v_exp_f32_e32 v15, v15
	v_exp_f32_e32 v16, v16
	v_exp_f32_e32 v17, v17
	v_exp_f32_e32 v6, v6
	v_exp_f32_e32 v7, v7
	v_exp_f32_e32 v8, v8
	v_exp_f32_e32 v9, v9
	v_pk_fma_f32 v[14:15], v[14:15], v[246:247], v[246:247] op_sel_hi:[1,0,0]
	v_pk_fma_f32 v[16:17], v[16:17], v[246:247], v[246:247] op_sel_hi:[1,0,0]
	v_pk_fma_f32 v[6:7], v[6:7], v[246:247], v[246:247] op_sel_hi:[1,0,0]
	v_pk_fma_f32 v[8:9], v[8:9], v[246:247], v[246:247] op_sel_hi:[1,0,0]
	v_rcp_f32_e32 v14, v14
	v_rcp_f32_e32 v15, v15
	v_rcp_f32_e32 v16, v16
	v_rcp_f32_e32 v17, v17
	v_rcp_f32_e32 v6, v6
	v_rcp_f32_e32 v7, v7
	v_rcp_f32_e32 v8, v8
	v_rcp_f32_e32 v9, v9
	v_pk_mul_f32 v[10:11], v[10:11], v[14:15]
	v_pk_mul_f32 v[12:13], v[12:13], v[16:17]
	v_pk_mul_f32 v[2:3], v[2:3], v[6:7]
	v_pk_mul_f32 v[4:5], v[4:5], v[8:9]
	v_cvt_pk_bf16_f32 v10, v10, v11
	v_cvt_pk_bf16_f32 v11, v12, v13
	v_cvt_pk_bf16_f32 v12, v2, v3
	v_cvt_pk_bf16_f32 v13, v4, v5
	global_store_dwordx4 v183, v[10:13], s[24:25] nt
	s_cbranch_vccnz .LBB0_605
	s_andn2_b64 vcc, exec, s[54:55]
	s_cbranch_vccnz .LBB0_604
	s_barrier
	s_branch .LBB0_604

; DI u32x4 pk8(f32x4 a, f32x4 b) { u32x4 w; w.x = pk2(a[0], a[1]); w.y = pk2(a[2], a[3]); w.z = pk2(b[0], b[1]); w.w = pk2(b[2], b[3]); return w; }
; DI float row_rstd(const float* SS, int row) { return rsqrtf(SS[row] * (1.0f / 1024.0f) + 1e-6f); }
;     DI void operator()(const Acc& acc, const pg8::Unit& u, int wr, int wc, int fr, int fq) const {
;         const int colb = u.pn * 128 + wc * 32 + fq * 8;
;         float rsv[2][4];
; #pragma unroll
;         for (int ai = 0; ai < 2; ++ai)
; #pragma unroll
;             for (int m = 0; m < 4; ++m) rsv[ai][m] = row_rstd(SS, u.pm * 256 + ai * 128 + wr * 64 + m * 16 + fr);
; #pragma unroll
;         for (int ai = 0; ai < 2; ++ai)
; #pragma unroll
;             for (int m = 0; m < 4; ++m) {
;                 const int row = u.pm * 256 + ai * 128 + wr * 64 + m * 16 + fr;
;                 const float rs = rsv[ai][m];
;                 f32x4 h0, h1;
;                 const float rs2 = rs * rs, nrl = -rs * LOG2E;
; #pragma unroll
;                 for (int i = 0; i < 4; ++i) {
;                     const float a0 = acc[ai][0][m][0][i], a1 = acc[ai][0][m][1][i];
;                     h0[i] = (a0 * acc[ai][1][m][0][i]) * rs2 * __builtin_amdgcn_rcpf(1.0f + __builtin_amdgcn_exp2f(a0 * nrl));
;                     h1[i] = (a1 * acc[ai][1][m][1][i]) * rs2 * __builtin_amdgcn_rcpf(1.0f + __builtin_amdgcn_exp2f(a1 * nrl));
;                 }
;                 __builtin_nontemporal_store(pk8(h0, h1), (u32x4*)(HID + (size_t)row * FH + colb));
;             }
.LBB0_1431:
	v_lshl_add_u32 v160, s4, 8, v165
	v_lshlrev_b32_e32 v185, 2, v160
	global_load_dword v146, v185, s[20:21]
	global_load_dword v147, v185, s[20:21] offset:64
	global_load_dword v148, v185, s[20:21] offset:128
	global_load_dword v149, v185, s[20:21] offset:192
	global_load_dword v150, v185, s[20:21] offset:512
	global_load_dword v151, v185, s[20:21] offset:576
	global_load_dword v152, v185, s[20:21] offset:640
	global_load_dword v153, v185, s[20:21] offset:704
	v_lshl_or_b32 v181, s5, 7, v167
	v_lshlrev_b32_e32 v181, 1, v181
	v_mad_u32_u24 v183, v160, s61, v181
	v_pk_mul_f32 v[122:123], v[126:127], v[122:123]
	v_pk_mul_f32 v[124:125], v[128:129], v[124:125]
	v_pk_mul_f32 v[114:115], v[118:119], v[114:115]
	v_pk_mul_f32 v[116:117], v[120:121], v[116:117]
	v_pk_mul_f32 v[106:107], v[110:111], v[106:107]
	v_pk_mul_f32 v[108:109], v[112:113], v[108:109]
	v_pk_mul_f32 v[98:99], v[102:103], v[98:99]
	v_pk_mul_f32 v[100:101], v[104:105], v[100:101]
	v_pk_mul_f32 v[90:91], v[94:95], v[90:91]
	v_pk_mul_f32 v[92:93], v[96:97], v[92:93]
	v_pk_mul_f32 v[82:83], v[86:87], v[82:83]
	v_pk_mul_f32 v[84:85], v[88:89], v[84:85]
	v_pk_mul_f32 v[74:75], v[78:79], v[74:75]
	v_pk_mul_f32 v[76:77], v[80:81], v[76:77]
	v_pk_mul_f32 v[66:67], v[70:71], v[66:67]
	v_pk_mul_f32 v[68:69], v[72:73], v[68:69]
	v_pk_mul_f32 v[58:59], v[62:63], v[58:59]
	v_pk_mul_f32 v[60:61], v[64:65], v[60:61]
	v_pk_mul_f32 v[50:51], v[54:55], v[50:51]
	v_pk_mul_f32 v[52:53], v[56:57], v[52:53]
	v_pk_mul_f32 v[42:43], v[46:47], v[42:43]
	v_pk_mul_f32 v[44:45], v[48:49], v[44:45]
	v_pk_mul_f32 v[34:35], v[38:39], v[34:35]
	v_pk_mul_f32 v[36:37], v[40:41], v[36:37]
	v_pk_mul_f32 v[26:27], v[30:31], v[26:27]
	v_pk_mul_f32 v[28:29], v[32:33], v[28:29]
	v_pk_mul_f32 v[18:19], v[22:23], v[18:19]
	v_pk_mul_f32 v[20:21], v[24:25], v[20:21]
	v_pk_mul_f32 v[10:11], v[14:15], v[10:11]
	v_pk_mul_f32 v[12:13], v[16:17], v[12:13]
	v_pk_mul_f32 v[2:3], v[6:7], v[2:3]
	v_pk_mul_f32 v[4:5], v[8:9], v[4:5]
	s_andn2_b64 vcc, exec, s[0:1]
	s_mov_b64 s[0:1], -1
	s_waitcnt vmcnt(0)
	v_fmamk_f32 v232, v146, 0x3a800000, v171
	v_fmamk_f32 v234, v147, 0x3a800000, v171
	v_fmamk_f32 v236, v148, 0x3a800000, v171
	v_fmamk_f32 v238, v149, 0x3a800000, v171
	v_fmamk_f32 v240, v150, 0x3a800000, v171
	v_fmamk_f32 v242, v151, 0x3a800000, v171
	v_fmamk_f32 v244, v152, 0x3a800000, v171
	v_fmamk_f32 v246, v153, 0x3a800000, v171
	v_rsq_f32_e32 v154, v232
	v_rsq_f32_e32 v155, v234
	v_rsq_f32_e32 v156, v236
	v_rsq_f32_e32 v157, v238
	v_rsq_f32_e32 v158, v240
	v_rsq_f32_e32 v159, v242
	v_rsq_f32_e32 v160, v244
	v_rsq_f32_e32 v161, v246
	v_mul_f32_e32 v172, 0xbfb8aa3b, v154
	v_mul_f32_e32 v174, 0xbfb8aa3b, v155
	v_mul_f32_e32 v176, 0xbfb8aa3b, v156
	v_mul_f32_e32 v178, 0xbfb8aa3b, v157
	v_mul_f32_e32 v180, 0xbfb8aa3b, v158
	v_mul_f32_e32 v182, 0xbfb8aa3b, v159
	v_mul_f32_e32 v184, 0xbfb8aa3b, v160
	v_mul_f32_e32 v230, 0xbfb8aa3b, v161
	v_pk_mul_f32 v[126:127], v[126:127], v[172:173] op_sel_hi:[1,0]
	v_pk_mul_f32 v[128:129], v[128:129], v[172:173] op_sel_hi:[1,0]
	v_pk_mul_f32 v[118:119], v[118:119], v[172:173] op_sel_hi:[1,0]
	v_pk_mul_f32 v[120:121], v[120:121], v[172:173] op_sel_hi:[1,0]
	v_exp_f32_e32 v126, v126
	v_exp_f32_e32 v127, v127
	v_exp_f32_e32 v128, v128
	v_exp_f32_e32 v129, v129
	v_exp_f32_e32 v118, v118
	v_exp_f32_e32 v119, v119
	v_exp_f32_e32 v120, v120
	v_exp_f32_e32 v121, v121
	v_pk_fma_f32 v[126:127], v[126:127], v[232:233], v[232:233] op_sel_hi:[1,0,0]
	v_pk_fma_f32 v[128:129], v[128:129], v[232:233], v[232:233] op_sel_hi:[1,0,0]
	v_pk_fma_f32 v[118:119], v[118:119], v[232:233], v[232:233] op_sel_hi:[1,0,0]
	v_pk_fma_f32 v[120:121], v[120:121], v[232:233], v[232:233] op_sel_hi:[1,0,0]
	v_rcp_f32_e32 v126, v126
	v_rcp_f32_e32 v127, v127
	v_rcp_f32_e32 v128, v128
	v_rcp_f32_e32 v129, v129
	v_rcp_f32_e32 v118, v118
	v_rcp_f32_e32 v119, v119
	v_rcp_f32_e32 v120, v120
	v_rcp_f32_e32 v121, v121
	v_pk_mul_f32 v[122:123], v[122:123], v[126:127]
	v_pk_mul_f32 v[124:125], v[124:125], v[128:129]
	v_pk_mul_f32 v[114:115], v[114:115], v[118:119]
	v_pk_mul_f32 v[116:117], v[116:117], v[120:121]
	v_cvt_pk_bf16_f32 v122, v122, v123
	v_cvt_pk_bf16_f32 v123, v124, v125
	v_cvt_pk_bf16_f32 v124, v114, v115
	v_cvt_pk_bf16_f32 v125, v116, v117
	global_store_dwordx4 v183, v[122:125], s[24:25] nt
	v_add_u32_e32 v183, 0x16000, v183
	v_pk_mul_f32 v[110:111], v[110:111], v[174:175] op_sel_hi:[1,0]
	v_pk_mul_f32 v[112:113], v[112:113], v[174:175] op_sel_hi:[1,0]
	v_pk_mul_f32 v[102:103], v[102:103], v[174:175] op_sel_hi:[1,0]
	v_pk_mul_f32 v[104:105], v[104:105], v[174:175] op_sel_hi:[1,0]
	v_exp_f32_e32 v110, v110
	v_exp_f32_e32 v111, v111
	v_exp_f32_e32 v112, v112
	v_exp_f32_e32 v113, v113
	v_exp_f32_e32 v102, v102
	v_exp_f32_e32 v103, v103
	v_exp_f32_e32 v104, v104
	v_exp_f32_e32 v105, v105
	v_pk_fma_f32 v[110:111], v[110:111], v[234:235], v[234:235] op_sel_hi:[1,0,0]
	v_pk_fma_f32 v[112:113], v[112:113], v[234:235], v[234:235] op_sel_hi:[1,0,0]
	v_pk_fma_f32 v[102:103], v[102:103], v[234:235], v[234:235] op_sel_hi:[1,0,0]
	v_pk_fma_f32 v[104:105], v[104:105], v[234:235], v[234:235] op_sel_hi:[1,0,0]
	v_rcp_f32_e32 v110, v110
	v_rcp_f32_e32 v111, v111
	v_rcp_f32_e32 v112, v112
	v_rcp_f32_e32 v113, v113
	v_rcp_f32_e32 v102, v102
	v_rcp_f32_e32 v103, v103
	v_rcp_f32_e32 v104, v104
	v_rcp_f32_e32 v105, v105
	v_pk_mul_f32 v[106:107], v[106:107], v[110:111]
	v_pk_mul_f32 v[108:109], v[108:109], v[112:113]
	v_pk_mul_f32 v[98:99], v[98:99], v[102:103]
	v_pk_mul_f32 v[100:101], v[100:101], v[104:105]
	v_cvt_pk_bf16_f32 v106, v106, v107
	v_cvt_pk_bf16_f32 v107, v108, v109
	v_cvt_pk_bf16_f32 v108, v98, v99
	v_cvt_pk_bf16_f32 v109, v100, v101
; DI u32x4 pk8(f32x4 a, f32x4 b) { u32x4 w; w.x = pk2(a[0], a[1]); w.y = pk2(a[2], a[3]); w.z = pk2(b[0], b[1]); w.w = pk2(b[2], b[3]); return w; }
; DI float row_rstd(const float* SS, int row) { return rsqrtf(SS[row] * (1.0f / 1024.0f) + 1e-6f); }
;     DI void operator()(const Acc& acc, const pg8::Unit& u, int wr, int wc, int fr, int fq) const {
;         const int colb = u.pn * 128 + wc * 32 + fq * 8;
;         float rsv[2][4];
; #pragma unroll
;         for (int ai = 0; ai < 2; ++ai)
; #pragma unroll
;             for (int m = 0; m < 4; ++m) rsv[ai][m] = row_rstd(SS, u.pm * 256 + ai * 128 + wr * 64 + m * 16 + fr);
; #pragma unroll
;         for (int ai = 0; ai < 2; ++ai)
; #pragma unroll
;             for (int m = 0; m < 4; ++m) {
;                 const int row = u.pm * 256 + ai * 128 + wr * 64 + m * 16 + fr;
;                 const float rs = rsv[ai][m];
;                 f32x4 h0, h1;
;                 const float rs2 = rs * rs, nrl = -rs * LOG2E;
; #pragma unroll
;                 for (int i = 0; i < 4; ++i) {
;                     const float a0 = acc[ai][0][m][0][i], a1 = acc[ai][0][m][1][i];
;                     h0[i] = (a0 * acc[ai][1][m][0][i]) * rs2 * __builtin_amdgcn_rcpf(1.0f + __builtin_amdgcn_exp2f(a0 * nrl));
;                     h1[i] = (a1 * acc[ai][1][m][1][i]) * rs2 * __builtin_amdgcn_rcpf(1.0f + __builtin_amdgcn_exp2f(a1 * nrl));
;                 }
;                 __builtin_nontemporal_store(pk8(h0, h1), (u32x4*)(HID + (size_t)row * FH + colb));
;             }
	global_store_dwordx4 v183, v[106:109], s[24:25] nt
	v_add_u32_e32 v183, 0x16000, v183
	v_pk_mul_f32 v[94:95], v[94:95], v[176:177] op_sel_hi:[1,0]
	v_pk_mul_f32 v[96:97], v[96:97], v[176:177] op_sel_hi:[1,0]
	v_pk_mul_f32 v[86:87], v[86:87], v[176:177] op_sel_hi:[1,0]
	v_pk_mul_f32 v[88:89], v[88:89], v[176:177] op_sel_hi:[1,0]
	v_exp_f32_e32 v94, v94
	v_exp_f32_e32 v95, v95
	v_exp_f32_e32 v96, v96
	v_exp_f32_e32 v97, v97
	v_exp_f32_e32 v86, v86
	v_exp_f32_e32 v87, v87
	v_exp_f32_e32 v88, v88
	v_exp_f32_e32 v89, v89
	v_pk_fma_f32 v[94:95], v[94:95], v[236:237], v[236:237] op_sel_hi:[1,0,0]
	v_pk_fma_f32 v[96:97], v[96:97], v[236:237], v[236:237] op_sel_hi:[1,0,0]
	v_pk_fma_f32 v[86:87], v[86:87], v[236:237], v[236:237] op_sel_hi:[1,0,0]
	v_pk_fma_f32 v[88:89], v[88:89], v[236:237], v[236:237] op_sel_hi:[1,0,0]
	v_rcp_f32_e32 v94, v94
	v_rcp_f32_e32 v95, v95
	v_rcp_f32_e32 v96, v96
	v_rcp_f32_e32 v97, v97
	v_rcp_f32_e32 v86, v86
	v_rcp_f32_e32 v87, v87
	v_rcp_f32_e32 v88, v88
	v_rcp_f32_e32 v89, v89
	v_pk_mul_f32 v[90:91], v[90:91], v[94:95]
	v_pk_mul_f32 v[92:93], v[92:93], v[96:97]
	v_pk_mul_f32 v[82:83], v[82:83], v[86:87]
	v_pk_mul_f32 v[84:85], v[84:85], v[88:89]
	v_cvt_pk_bf16_f32 v90, v90, v91
	v_cvt_pk_bf16_f32 v91, v92, v93
	v_cvt_pk_bf16_f32 v92, v82, v83
	v_cvt_pk_bf16_f32 v93, v84, v85
	global_store_dwordx4 v183, v[90:93], s[24:25] nt
	v_add_u32_e32 v183, 0x16000, v183
	v_pk_mul_f32 v[78:79], v[78:79], v[178:179] op_sel_hi:[1,0]
	v_pk_mul_f32 v[80:81], v[80:81], v[178:179] op_sel_hi:[1,0]
	v_pk_mul_f32 v[70:71], v[70:71], v[178:179] op_sel_hi:[1,0]
	v_pk_mul_f32 v[72:73], v[72:73], v[178:179] op_sel_hi:[1,0]
	v_exp_f32_e32 v78, v78
	v_exp_f32_e32 v79, v79
	v_exp_f32_e32 v80, v80
	v_exp_f32_e32 v81, v81
	v_exp_f32_e32 v70, v70
	v_exp_f32_e32 v71, v71
	v_exp_f32_e32 v72, v72
	v_exp_f32_e32 v73, v73
	v_pk_fma_f32 v[78:79], v[78:79], v[238:239], v[238:239] op_sel_hi:[1,0,0]
	v_pk_fma_f32 v[80:81], v[80:81], v[238:239], v[238:239] op_sel_hi:[1,0,0]
	v_pk_fma_f32 v[70:71], v[70:71], v[238:239], v[238:239] op_sel_hi:[1,0,0]
	v_pk_fma_f32 v[72:73], v[72:73], v[238:239], v[238:239] op_sel_hi:[1,0,0]
	v_rcp_f32_e32 v78, v78
	v_rcp_f32_e32 v79, v79
	v_rcp_f32_e32 v80, v80
	v_rcp_f32_e32 v81, v81
	v_rcp_f32_e32 v70, v70
	v_rcp_f32_e32 v71, v71
	v_rcp_f32_e32 v72, v72
	v_rcp_f32_e32 v73, v73
	v_pk_mul_f32 v[74:75], v[74:75], v[78:79]
	v_pk_mul_f32 v[76:77], v[76:77], v[80:81]
	v_pk_mul_f32 v[66:67], v[66:67], v[70:71]
	v_pk_mul_f32 v[68:69], v[68:69], v[72:73]
	v_cvt_pk_bf16_f32 v74, v74, v75
	v_cvt_pk_bf16_f32 v75, v76, v77
	v_cvt_pk_bf16_f32 v76, v66, v67
	v_cvt_pk_bf16_f32 v77, v68, v69
	global_store_dwordx4 v183, v[74:77], s[24:25] nt
	v_add_u32_e32 v183, 0x6e000, v183
	v_pk_mul_f32 v[62:63], v[62:63], v[180:181] op_sel_hi:[1,0]
	v_pk_mul_f32 v[64:65], v[64:65], v[180:181] op_sel_hi:[1,0]
	v_pk_mul_f32 v[54:55], v[54:55], v[180:181] op_sel_hi:[1,0]
	v_pk_mul_f32 v[56:57], v[56:57], v[180:181] op_sel_hi:[1,0]
	v_exp_f32_e32 v62, v62
	v_exp_f32_e32 v63, v63
	v_exp_f32_e32 v64, v64
	v_exp_f32_e32 v65, v65
	v_exp_f32_e32 v54, v54
	v_exp_f32_e32 v55, v55
	v_exp_f32_e32 v56, v56
	v_exp_f32_e32 v57, v57
	v_pk_fma_f32 v[62:63], v[62:63], v[240:241], v[240:241] op_sel_hi:[1,0,0]
	v_pk_fma_f32 v[64:65], v[64:65], v[240:241], v[240:241] op_sel_hi:[1,0,0]
	v_pk_fma_f32 v[54:55], v[54:55], v[240:241], v[240:241] op_sel_hi:[1,0,0]
	v_pk_fma_f32 v[56:57], v[56:57], v[240:241], v[240:241] op_sel_hi:[1,0,0]
	v_rcp_f32_e32 v62, v62
	v_rcp_f32_e32 v63, v63
	v_rcp_f32_e32 v64, v64
	v_rcp_f32_e32 v65, v65
	v_rcp_f32_e32 v54, v54
	v_rcp_f32_e32 v55, v55
	v_rcp_f32_e32 v56, v56
	v_rcp_f32_e32 v57, v57
	v_pk_mul_f32 v[58:59], v[58:59], v[62:63]
	v_pk_mul_f32 v[60:61], v[60:61], v[64:65]
	v_pk_mul_f32 v[50:51], v[50:51], v[54:55]
	v_pk_mul_f32 v[52:53], v[52:53], v[56:57]
	v_cvt_pk_bf16_f32 v58, v58, v59
	v_cvt_pk_bf16_f32 v59, v60, v61
	v_cvt_pk_bf16_f32 v60, v50, v51
	v_cvt_pk_bf16_f32 v61, v52, v53
	global_store_dwordx4 v183, v[58:61], s[24:25] nt
; DI u32x4 pk8(f32x4 a, f32x4 b) { u32x4 w; w.x = pk2(a[0], a[1]); w.y = pk2(a[2], a[3]); w.z = pk2(b[0], b[1]); w.w = pk2(b[2], b[3]); return w; }
; #define PG8_BAR __builtin_amdgcn_s_barrier()
; DI float row_rstd(const float* SS, int row) { return rsqrtf(SS[row] * (1.0f / 1024.0f) + 1e-6f); }
; template <class Epi, bool ALIGN_EPI>
; __device__ __forceinline__ void gemm_phase(LAS unsigned char* lds, const Gemm g, const StaticOrder& S, const Epi& E) {
;     ...
;         if (!has_next) break;
; #pragma unroll
;         for (int a = 0; a < 2; ++a)
; #pragma unroll
;             for (int b = 0; b < 2; ++b)
; #pragma unroll
;                 for (int m = 0; m < 4; ++m)
; #pragma unroll
;                     for (int n = 0; n < 2; ++n) acc[a][b][m][n] = (f32x4){0.f, 0.f, 0.f, 0.f};
;         cur = nxt; cA = nA; cB = nB; ++ui;
;         if constexpr (ALIGN_EPI) { if (wr == 1) PG8_BAR; }
;     DI void operator()(const Acc& acc, const pg8::Unit& u, int wr, int wc, int fr, int fq) const {
;         const int colb = u.pn * 128 + wc * 32 + fq * 8;
;         float rsv[2][4];
; #pragma unroll
;         for (int ai = 0; ai < 2; ++ai)
; #pragma unroll
;             for (int m = 0; m < 4; ++m) rsv[ai][m] = row_rstd(SS, u.pm * 256 + ai * 128 + wr * 64 + m * 16 + fr);
; #pragma unroll
;         for (int ai = 0; ai < 2; ++ai)
; #pragma unroll
;             for (int m = 0; m < 4; ++m) {
;                 const int row = u.pm * 256 + ai * 128 + wr * 64 + m * 16 + fr;
;                 const float rs = rsv[ai][m];
;                 f32x4 h0, h1;
;                 const float rs2 = rs * rs, nrl = -rs * LOG2E;
; #pragma unroll
;                 for (int i = 0; i < 4; ++i) {
;                     const float a0 = acc[ai][0][m][0][i], a1 = acc[ai][0][m][1][i];
;                     h0[i] = (a0 * acc[ai][1][m][0][i]) * rs2 * __builtin_amdgcn_rcpf(1.0f + __builtin_amdgcn_exp2f(a0 * nrl));
;                     h1[i] = (a1 * acc[ai][1][m][1][i]) * rs2 * __builtin_amdgcn_rcpf(1.0f + __builtin_amdgcn_exp2f(a1 * nrl));
;                 }
;                 __builtin_nontemporal_store(pk8(h0, h1), (u32x4*)(HID + (size_t)row * FH + colb));
;             }
	v_add_u32_e32 v183, 0x16000, v183
	v_pk_mul_f32 v[46:47], v[46:47], v[182:183] op_sel_hi:[1,0]
	v_pk_mul_f32 v[48:49], v[48:49], v[182:183] op_sel_hi:[1,0]
	v_pk_mul_f32 v[38:39], v[38:39], v[182:183] op_sel_hi:[1,0]
	v_pk_mul_f32 v[40:41], v[40:41], v[182:183] op_sel_hi:[1,0]
	v_exp_f32_e32 v46, v46
	v_exp_f32_e32 v47, v47
	v_exp_f32_e32 v48, v48
	v_exp_f32_e32 v49, v49
	v_exp_f32_e32 v38, v38
	v_exp_f32_e32 v39, v39
	v_exp_f32_e32 v40, v40
	v_exp_f32_e32 v41, v41
	v_pk_fma_f32 v[46:47], v[46:47], v[242:243], v[242:243] op_sel_hi:[1,0,0]
	v_pk_fma_f32 v[48:49], v[48:49], v[242:243], v[242:243] op_sel_hi:[1,0,0]
	v_pk_fma_f32 v[38:39], v[38:39], v[242:243], v[242:243] op_sel_hi:[1,0,0]
	v_pk_fma_f32 v[40:41], v[40:41], v[242:243], v[242:243] op_sel_hi:[1,0,0]
	v_rcp_f32_e32 v46, v46
	v_rcp_f32_e32 v47, v47
	v_rcp_f32_e32 v48, v48
	v_rcp_f32_e32 v49, v49
	v_rcp_f32_e32 v38, v38
	v_rcp_f32_e32 v39, v39
	v_rcp_f32_e32 v40, v40
	v_rcp_f32_e32 v41, v41
	v_pk_mul_f32 v[42:43], v[42:43], v[46:47]
	v_pk_mul_f32 v[44:45], v[44:45], v[48:49]
	v_pk_mul_f32 v[34:35], v[34:35], v[38:39]
	v_pk_mul_f32 v[36:37], v[36:37], v[40:41]
	v_cvt_pk_bf16_f32 v42, v42, v43
	v_cvt_pk_bf16_f32 v43, v44, v45
	v_cvt_pk_bf16_f32 v44, v34, v35
	v_cvt_pk_bf16_f32 v45, v36, v37
	global_store_dwordx4 v183, v[42:45], s[24:25] nt
	v_add_u32_e32 v183, 0x16000, v183
	v_pk_mul_f32 v[30:31], v[30:31], v[184:185] op_sel_hi:[1,0]
	v_pk_mul_f32 v[32:33], v[32:33], v[184:185] op_sel_hi:[1,0]
	v_pk_mul_f32 v[22:23], v[22:23], v[184:185] op_sel_hi:[1,0]
	v_pk_mul_f32 v[24:25], v[24:25], v[184:185] op_sel_hi:[1,0]
	v_exp_f32_e32 v30, v30
	v_exp_f32_e32 v31, v31
	v_exp_f32_e32 v32, v32
	v_exp_f32_e32 v33, v33
	v_exp_f32_e32 v22, v22
	v_exp_f32_e32 v23, v23
	v_exp_f32_e32 v24, v24
	v_exp_f32_e32 v25, v25
	v_pk_fma_f32 v[30:31], v[30:31], v[244:245], v[244:245] op_sel_hi:[1,0,0]
	v_pk_fma_f32 v[32:33], v[32:33], v[244:245], v[244:245] op_sel_hi:[1,0,0]
	v_pk_fma_f32 v[22:23], v[22:23], v[244:245], v[244:245] op_sel_hi:[1,0,0]
	v_pk_fma_f32 v[24:25], v[24:25], v[244:245], v[244:245] op_sel_hi:[1,0,0]
	v_rcp_f32_e32 v30, v30
	v_rcp_f32_e32 v31, v31
	v_rcp_f32_e32 v32, v32
	v_rcp_f32_e32 v33, v33
	v_rcp_f32_e32 v22, v22
	v_rcp_f32_e32 v23, v23
	v_rcp_f32_e32 v24, v24
	v_rcp_f32_e32 v25, v25
	v_pk_mul_f32 v[26:27], v[26:27], v[30:31]
	v_pk_mul_f32 v[28:29], v[28:29], v[32:33]
	v_pk_mul_f32 v[18:19], v[18:19], v[22:23]
	v_pk_mul_f32 v[20:21], v[20:21], v[24:25]
	v_cvt_pk_bf16_f32 v26, v26, v27
	v_cvt_pk_bf16_f32 v27, v28, v29
	v_cvt_pk_bf16_f32 v28, v18, v19
	v_cvt_pk_bf16_f32 v29, v20, v21
	global_store_dwordx4 v183, v[26:29], s[24:25] nt
	v_add_u32_e32 v183, 0x16000, v183
	v_pk_mul_f32 v[14:15], v[14:15], v[230:231] op_sel_hi:[1,0]
	v_pk_mul_f32 v[16:17], v[16:17], v[230:231] op_sel_hi:[1,0]
	v_pk_mul_f32 v[6:7], v[6:7], v[230:231] op_sel_hi:[1,0]
	v_pk_mul_f32 v[8:9], v[8:9], v[230:231] op_sel_hi:[1,0]
	v_exp_f32_e32 v14, v14
	v_exp_f32_e32 v15, v15
	v_exp_f32_e32 v16, v16
	v_exp_f32_e32 v17, v17
	v_exp_f32_e32 v6, v6
	v_exp_f32_e32 v7, v7
	v_exp_f32_e32 v8, v8
	v_exp_f32_e32 v9, v9
	v_pk_fma_f32 v[14:15], v[14:15], v[246:247], v[246:247] op_sel_hi:[1,0,0]
	v_pk_fma_f32 v[16:17], v[16:17], v[246:247], v[246:247] op_sel_hi:[1,0,0]
	v_pk_fma_f32 v[6:7], v[6:7], v[246:247], v[246:247] op_sel_hi:[1,0,0]
	v_pk_fma_f32 v[8:9], v[8:9], v[246:247], v[246:247] op_sel_hi:[1,0,0]
	v_rcp_f32_e32 v14, v14
	v_rcp_f32_e32 v15, v15
	v_rcp_f32_e32 v16, v16
	v_rcp_f32_e32 v17, v17
	v_rcp_f32_e32 v6, v6
	v_rcp_f32_e32 v7, v7
	v_rcp_f32_e32 v8, v8
	v_rcp_f32_e32 v9, v9
	v_pk_mul_f32 v[10:11], v[10:11], v[14:15]
	v_pk_mul_f32 v[12:13], v[12:13], v[16:17]
	v_pk_mul_f32 v[2:3], v[2:3], v[6:7]
	v_pk_mul_f32 v[4:5], v[4:5], v[8:9]
	v_cvt_pk_bf16_f32 v10, v10, v11
	v_cvt_pk_bf16_f32 v11, v12, v13
	v_cvt_pk_bf16_f32 v12, v2, v3
	v_cvt_pk_bf16_f32 v13, v4, v5
	global_store_dwordx4 v183, v[10:13], s[24:25] nt
	s_cbranch_vccnz .LBB0_1424
	s_andn2_b64 vcc, exec, s[26:27]
	s_cbranch_vccnz .LBB0_1423
	s_barrier
	s_branch .LBB0_1423
